# merge phase: 7 blocks of the running merged tile in registers + 3 blocks in 24 KB of static LDS (10 of 16 blocks no longer read-modify-written through memory)
# speedup vs baseline: 1.0318x; 1.0125x over previous
.LBB0_1020:
	s_lshl_b32 s13, s20, 8
	s_lshl_b32 s20, s5, 10
	v_mbcnt_lo_u32_b32 v236, -1, 0
	v_mbcnt_hi_u32_b32 v236, -1, v236
	s_lshl_b32 s4, s4, 8
	v_and_or_b32 v176, v236, 15, s45
	s_ashr_i32 s21, s20, 31
	v_ashrrev_i32_e32 v236, 1, v236
	v_add_u32_e32 v168, s13, v176
	s_or_b32 s4, s4, s46
	s_lshl_b64 s[20:21], s[20:21], 1
	v_and_b32_e32 v236, -8, v236
	s_add_u32 s20, s43, s20
	v_ashrrev_i32_e32 v169, 31, v168
	v_add_u32_e32 v166, s4, v236
	s_addc_u32 s21, s44, s21
	v_lshlrev_b64 v[236:237], 13, v[168:169]
	v_lshl_add_u64 v[236:237], s[20:21], 0, v[236:237]
	v_ashrrev_i32_e32 v167, 31, v166
	v_lshl_add_u64 v[236:237], v[166:167], 1, v[236:237]
	v_lshlrev_b64 v[238:239], 11, v[168:169]
	v_lshl_add_u64 v[238:239], s[8:9], 0, v[238:239]
	v_lshl_add_u64 v[172:173], v[166:167], 1, v[238:239]
	v_mov_b64_e32 v[170:171], v[236:237]
	v_mov_b64_e32 v[230:231], v[250:251]
	v_mov_b32_e32 v243, v249
	v_mov_b32_e32 v251, v248
	v_mov_b32_e32 v249, 0x358637bd
	v_mov_b32_e32 v248, 0x260
	s_mov_b32 s59, 0
	s_waitcnt lgkmcnt(0)
	v_mbcnt_lo_u32_b32 v177, -1, 0
	v_mbcnt_hi_u32_b32 v177, -1, v177
	s_lshl_b32 s58, s45, 6
	s_lshl_b32 s59, s46, 5
	s_add_i32 s58, s58, s59
	s_add_i32 s58, s58, 0x21000
	s_mov_b32 s59, 0
	v_lshl_add_u32 v177, v177, 4, s58
	s_cmp_eq_u32 s5, 0
	s_cbranch_scc1 .Lmepi_z0
	s_cmp_eq_u32 s5, 3
	s_cbranch_scc1 .Lmepi_z3
	global_load_dwordx4 v[128:131], v[170:171], off nt
	global_load_dwordx4 v[132:135], v[170:171], off offset:256 nt
	s_mov_b32 s58, 0x20000
	v_lshl_add_u64 v[244:245], v[170:171], 0, s[58:59]
	global_load_dwordx4 v[136:139], v[244:245], off nt
	global_load_dwordx4 v[140:143], v[244:245], off offset:256 nt
	s_mov_b32 s58, 0x40000
	v_lshl_add_u64 v[246:247], v[170:171], 0, s[58:59]
	global_load_dwordx4 v[144:147], v[246:247], off nt
	global_load_dwordx4 v[148:151], v[246:247], off offset:256 nt
	s_mov_b32 s58, 0x60000
	v_lshl_add_u64 v[252:253], v[170:171], 0, s[58:59]
	global_load_dwordx4 v[152:155], v[252:253], off nt
	global_load_dwordx4 v[156:159], v[252:253], off offset:256 nt
	ds_read_b128 v[180:183], v177 offset:0
	s_mov_b32 s58, 0x100000
	v_lshl_add_u64 v[178:179], v[170:171], 0, s[58:59]
	global_load_dwordx4 v[184:187], v[178:179], off nt
	global_load_dwordx4 v[188:191], v[178:179], off offset:256 nt
	ds_read_b128 v[192:195], v177 offset:8192
	ds_read_b128 v[196:199], v177 offset:16384
	s_waitcnt vmcnt(9)
	v_lshlrev_b32_e32 v240, 16, v128
	v_and_b32_e32 v241, 0xffff0000, v128
	v_pk_mul_f32 v[0:1], v[0:1], v[240:241]
	v_lshlrev_b32_e32 v244, 16, v129
	v_and_b32_e32 v245, 0xffff0000, v129
	v_pk_mul_f32 v[2:3], v[2:3], v[244:245]
	v_lshlrev_b32_e32 v246, 16, v130
	v_and_b32_e32 v247, 0xffff0000, v130
	v_pk_mul_f32 v[4:5], v[4:5], v[246:247]
	v_lshlrev_b32_e32 v252, 16, v131
	v_and_b32_e32 v253, 0xffff0000, v131
	v_pk_mul_f32 v[6:7], v[6:7], v[252:253]
	v_lshlrev_b32_e32 v178, 16, v200
	v_and_b32_e32 v179, 0xffff0000, v200
	v_pk_add_f32 v[0:1], v[0:1], v[178:179]
	v_lshlrev_b32_e32 v240, 16, v201
	v_and_b32_e32 v241, 0xffff0000, v201
	v_pk_add_f32 v[2:3], v[2:3], v[240:241]
	v_lshlrev_b32_e32 v244, 16, v202
	v_and_b32_e32 v245, 0xffff0000, v202
	v_pk_add_f32 v[4:5], v[4:5], v[244:245]
	v_lshlrev_b32_e32 v246, 16, v203
	v_and_b32_e32 v247, 0xffff0000, v203
	v_pk_add_f32 v[6:7], v[6:7], v[246:247]
	v_cvt_pk_bf16_f32 v200, v0, v1
	v_cvt_pk_bf16_f32 v201, v2, v3
	v_cvt_pk_bf16_f32 v202, v4, v5
	v_cvt_pk_bf16_f32 v203, v6, v7
	s_waitcnt vmcnt(8)
	v_lshlrev_b32_e32 v252, 16, v132
	v_and_b32_e32 v253, 0xffff0000, v132
	v_pk_mul_f32 v[8:9], v[8:9], v[252:253]
	v_lshlrev_b32_e32 v178, 16, v133
	v_and_b32_e32 v179, 0xffff0000, v133
	v_pk_mul_f32 v[10:11], v[10:11], v[178:179]
	v_lshlrev_b32_e32 v240, 16, v134
	v_and_b32_e32 v241, 0xffff0000, v134
	v_pk_mul_f32 v[12:13], v[12:13], v[240:241]
	v_lshlrev_b32_e32 v244, 16, v135
	v_and_b32_e32 v245, 0xffff0000, v135
	v_pk_mul_f32 v[14:15], v[14:15], v[244:245]
	v_lshlrev_b32_e32 v246, 16, v204
	v_and_b32_e32 v247, 0xffff0000, v204
	v_pk_add_f32 v[8:9], v[8:9], v[246:247]
	v_lshlrev_b32_e32 v252, 16, v205
	v_and_b32_e32 v253, 0xffff0000, v205
	v_pk_add_f32 v[10:11], v[10:11], v[252:253]
	v_lshlrev_b32_e32 v178, 16, v206
	v_and_b32_e32 v179, 0xffff0000, v206
	v_pk_add_f32 v[12:13], v[12:13], v[178:179]
	v_lshlrev_b32_e32 v240, 16, v207
	v_and_b32_e32 v241, 0xffff0000, v207
	v_pk_add_f32 v[14:15], v[14:15], v[240:241]
	v_cvt_pk_bf16_f32 v204, v8, v9
	v_cvt_pk_bf16_f32 v205, v10, v11
	v_cvt_pk_bf16_f32 v206, v12, v13
	v_cvt_pk_bf16_f32 v207, v14, v15
	s_mov_b32 s58, 0x120000
	v_lshl_add_u64 v[244:245], v[170:171], 0, s[58:59]
	global_load_dwordx4 v[236:239], v[244:245], off nt
	global_load_dwordx4 v[0:3], v[244:245], off offset:256 nt
	s_mov_b32 s58, 0x48000
	v_lshl_add_u64 v[246:247], v[172:173], 0, s[58:59]
	global_load_dwordx4 v[4:7], v[246:247], off
	global_load_dwordx4 v[128:131], v[246:247], off offset:256
	s_waitcnt vmcnt(11)
	v_lshlrev_b32_e32 v252, 16, v136
	v_and_b32_e32 v253, 0xffff0000, v136
	v_pk_mul_f32 v[16:17], v[16:17], v[252:253]
	v_lshlrev_b32_e32 v178, 16, v137
	v_and_b32_e32 v179, 0xffff0000, v137
	v_pk_mul_f32 v[18:19], v[18:19], v[178:179]
	v_lshlrev_b32_e32 v240, 16, v138
	v_and_b32_e32 v241, 0xffff0000, v138
	v_pk_mul_f32 v[20:21], v[20:21], v[240:241]
	v_lshlrev_b32_e32 v244, 16, v139
	v_and_b32_e32 v245, 0xffff0000, v139
	v_pk_mul_f32 v[22:23], v[22:23], v[244:245]
	v_lshlrev_b32_e32 v246, 16, v208
	v_and_b32_e32 v247, 0xffff0000, v208
	v_pk_add_f32 v[16:17], v[16:17], v[246:247]
	v_lshlrev_b32_e32 v252, 16, v209
	v_and_b32_e32 v253, 0xffff0000, v209
	v_pk_add_f32 v[18:19], v[18:19], v[252:253]
	v_lshlrev_b32_e32 v178, 16, v210
	v_and_b32_e32 v179, 0xffff0000, v210
	v_pk_add_f32 v[20:21], v[20:21], v[178:179]
	v_lshlrev_b32_e32 v240, 16, v211
	v_and_b32_e32 v241, 0xffff0000, v211
	v_pk_add_f32 v[22:23], v[22:23], v[240:241]
	v_cvt_pk_bf16_f32 v208, v16, v17
	v_cvt_pk_bf16_f32 v209, v18, v19
	v_cvt_pk_bf16_f32 v210, v20, v21
	v_cvt_pk_bf16_f32 v211, v22, v23
	s_waitcnt vmcnt(10)
	v_lshlrev_b32_e32 v244, 16, v140
	v_and_b32_e32 v245, 0xffff0000, v140
	v_pk_mul_f32 v[24:25], v[24:25], v[244:245]
	v_lshlrev_b32_e32 v246, 16, v141
	v_and_b32_e32 v247, 0xffff0000, v141
	v_pk_mul_f32 v[26:27], v[26:27], v[246:247]
	v_lshlrev_b32_e32 v252, 16, v142
	v_and_b32_e32 v253, 0xffff0000, v142
	v_pk_mul_f32 v[28:29], v[28:29], v[252:253]
	v_lshlrev_b32_e32 v178, 16, v143
	v_and_b32_e32 v179, 0xffff0000, v143
	v_pk_mul_f32 v[30:31], v[30:31], v[178:179]
	v_lshlrev_b32_e32 v240, 16, v212
	v_and_b32_e32 v241, 0xffff0000, v212
	v_pk_add_f32 v[24:25], v[24:25], v[240:241]
	v_lshlrev_b32_e32 v244, 16, v213
	v_and_b32_e32 v245, 0xffff0000, v213
	v_pk_add_f32 v[26:27], v[26:27], v[244:245]
	v_lshlrev_b32_e32 v246, 16, v214
	v_and_b32_e32 v247, 0xffff0000, v214
	v_pk_add_f32 v[28:29], v[28:29], v[246:247]
	v_lshlrev_b32_e32 v252, 16, v215
	v_and_b32_e32 v253, 0xffff0000, v215
	v_pk_add_f32 v[30:31], v[30:31], v[252:253]
	v_cvt_pk_bf16_f32 v212, v24, v25
	v_cvt_pk_bf16_f32 v213, v26, v27
	v_cvt_pk_bf16_f32 v214, v28, v29
	v_cvt_pk_bf16_f32 v215, v30, v31
	s_mov_b32 s58, 0x140000
	v_lshl_add_u64 v[178:179], v[170:171], 0, s[58:59]
	global_load_dwordx4 v[8:11], v[178:179], off nt
	global_load_dwordx4 v[12:15], v[178:179], off offset:256 nt
	s_mov_b32 s58, 0x50000
	v_lshl_add_u64 v[240:241], v[172:173], 0, s[58:59]
	global_load_dwordx4 v[132:135], v[240:241], off
	global_load_dwordx4 v[16:19], v[240:241], off offset:256
	s_mov_b32 s58, 0x160000
	v_lshl_add_u64 v[244:245], v[170:171], 0, s[58:59]
	global_load_dwordx4 v[20:23], v[244:245], off nt
	global_load_dwordx4 v[136:139], v[244:245], off offset:256 nt
	s_mov_b32 s58, 0x58000
	v_lshl_add_u64 v[246:247], v[172:173], 0, s[58:59]
	global_load_dwordx4 v[24:27], v[246:247], off
	global_load_dwordx4 v[28:31], v[246:247], off offset:256
	s_waitcnt vmcnt(17)
	v_lshlrev_b32_e32 v252, 16, v144
	v_and_b32_e32 v253, 0xffff0000, v144
	v_pk_mul_f32 v[32:33], v[32:33], v[252:253]
	v_lshlrev_b32_e32 v178, 16, v145
	v_and_b32_e32 v179, 0xffff0000, v145
	v_pk_mul_f32 v[34:35], v[34:35], v[178:179]
	v_lshlrev_b32_e32 v240, 16, v146
	v_and_b32_e32 v241, 0xffff0000, v146
	v_pk_mul_f32 v[36:37], v[36:37], v[240:241]
	v_lshlrev_b32_e32 v244, 16, v147
	v_and_b32_e32 v245, 0xffff0000, v147
	v_pk_mul_f32 v[38:39], v[38:39], v[244:245]
	v_lshlrev_b32_e32 v246, 16, v216
	v_and_b32_e32 v247, 0xffff0000, v216
	v_pk_add_f32 v[32:33], v[32:33], v[246:247]
	v_lshlrev_b32_e32 v252, 16, v217
	v_and_b32_e32 v253, 0xffff0000, v217
	v_pk_add_f32 v[34:35], v[34:35], v[252:253]
	v_lshlrev_b32_e32 v178, 16, v218
	v_and_b32_e32 v179, 0xffff0000, v218
	v_pk_add_f32 v[36:37], v[36:37], v[178:179]
	v_lshlrev_b32_e32 v240, 16, v219
	v_and_b32_e32 v241, 0xffff0000, v219
	v_pk_add_f32 v[38:39], v[38:39], v[240:241]
	v_cvt_pk_bf16_f32 v216, v32, v33
	v_cvt_pk_bf16_f32 v217, v34, v35
	v_cvt_pk_bf16_f32 v218, v36, v37
	v_cvt_pk_bf16_f32 v219, v38, v39
	s_waitcnt vmcnt(16)
	v_lshlrev_b32_e32 v244, 16, v148
	v_and_b32_e32 v245, 0xffff0000, v148
	v_pk_mul_f32 v[40:41], v[40:41], v[244:245]
	v_lshlrev_b32_e32 v246, 16, v149
	v_and_b32_e32 v247, 0xffff0000, v149
	v_pk_mul_f32 v[42:43], v[42:43], v[246:247]
	v_lshlrev_b32_e32 v252, 16, v150
	v_and_b32_e32 v253, 0xffff0000, v150
	v_pk_mul_f32 v[44:45], v[44:45], v[252:253]
	v_lshlrev_b32_e32 v178, 16, v151
	v_and_b32_e32 v179, 0xffff0000, v151
	v_pk_mul_f32 v[46:47], v[46:47], v[178:179]
	v_lshlrev_b32_e32 v240, 16, v220
	v_and_b32_e32 v241, 0xffff0000, v220
	v_pk_add_f32 v[40:41], v[40:41], v[240:241]
	v_lshlrev_b32_e32 v244, 16, v221
	v_and_b32_e32 v245, 0xffff0000, v221
	v_pk_add_f32 v[42:43], v[42:43], v[244:245]
	v_lshlrev_b32_e32 v246, 16, v222
	v_and_b32_e32 v247, 0xffff0000, v222
	v_pk_add_f32 v[44:45], v[44:45], v[246:247]
	v_lshlrev_b32_e32 v252, 16, v223
	v_and_b32_e32 v253, 0xffff0000, v223
	v_pk_add_f32 v[46:47], v[46:47], v[252:253]
	v_cvt_pk_bf16_f32 v220, v40, v41
	v_cvt_pk_bf16_f32 v221, v42, v43
	v_cvt_pk_bf16_f32 v222, v44, v45
	v_cvt_pk_bf16_f32 v223, v46, v47
	s_waitcnt vmcnt(15)
	v_lshlrev_b32_e32 v178, 16, v152
	v_and_b32_e32 v179, 0xffff0000, v152
	v_pk_mul_f32 v[48:49], v[48:49], v[178:179]
	v_lshlrev_b32_e32 v240, 16, v153
	v_and_b32_e32 v241, 0xffff0000, v153
	v_pk_mul_f32 v[50:51], v[50:51], v[240:241]
	v_lshlrev_b32_e32 v244, 16, v154
	v_and_b32_e32 v245, 0xffff0000, v154
	v_pk_mul_f32 v[52:53], v[52:53], v[244:245]
	v_lshlrev_b32_e32 v246, 16, v155
	v_and_b32_e32 v247, 0xffff0000, v155
	v_pk_mul_f32 v[54:55], v[54:55], v[246:247]
	v_lshlrev_b32_e32 v252, 16, v224
	v_and_b32_e32 v253, 0xffff0000, v224
	v_pk_add_f32 v[48:49], v[48:49], v[252:253]
	v_lshlrev_b32_e32 v178, 16, v225
	v_and_b32_e32 v179, 0xffff0000, v225
	v_pk_add_f32 v[50:51], v[50:51], v[178:179]
	v_lshlrev_b32_e32 v240, 16, v226
	v_and_b32_e32 v241, 0xffff0000, v226
	v_pk_add_f32 v[52:53], v[52:53], v[240:241]
	v_lshlrev_b32_e32 v244, 16, v227
	v_and_b32_e32 v245, 0xffff0000, v227
	v_pk_add_f32 v[54:55], v[54:55], v[244:245]
	v_cvt_pk_bf16_f32 v224, v48, v49
	v_cvt_pk_bf16_f32 v225, v50, v51
	v_cvt_pk_bf16_f32 v226, v52, v53
	v_cvt_pk_bf16_f32 v227, v54, v55
	s_waitcnt vmcnt(14)
	s_waitcnt lgkmcnt(0)
	v_lshlrev_b32_e32 v246, 16, v156
	v_and_b32_e32 v247, 0xffff0000, v156
	v_pk_mul_f32 v[56:57], v[56:57], v[246:247]
	v_lshlrev_b32_e32 v252, 16, v157
	v_and_b32_e32 v253, 0xffff0000, v157
	v_pk_mul_f32 v[58:59], v[58:59], v[252:253]
	v_lshlrev_b32_e32 v178, 16, v158
	v_and_b32_e32 v179, 0xffff0000, v158
	v_pk_mul_f32 v[60:61], v[60:61], v[178:179]
	v_lshlrev_b32_e32 v240, 16, v159
	v_and_b32_e32 v241, 0xffff0000, v159
	v_pk_mul_f32 v[62:63], v[62:63], v[240:241]
	v_lshlrev_b32_e32 v244, 16, v180
	v_and_b32_e32 v245, 0xffff0000, v180
	v_pk_add_f32 v[56:57], v[56:57], v[244:245]
	v_lshlrev_b32_e32 v246, 16, v181
	v_and_b32_e32 v247, 0xffff0000, v181
	v_pk_add_f32 v[58:59], v[58:59], v[246:247]
	v_lshlrev_b32_e32 v252, 16, v182
	v_and_b32_e32 v253, 0xffff0000, v182
	v_pk_add_f32 v[60:61], v[60:61], v[252:253]
	v_lshlrev_b32_e32 v178, 16, v183
	v_and_b32_e32 v179, 0xffff0000, v183
	v_pk_add_f32 v[62:63], v[62:63], v[178:179]
	v_cvt_pk_bf16_f32 v156, v56, v57
	v_cvt_pk_bf16_f32 v157, v58, v59
	v_cvt_pk_bf16_f32 v158, v60, v61
	v_cvt_pk_bf16_f32 v159, v62, v63
	ds_write_b128 v177, v[156:159] offset:0
	s_waitcnt lgkmcnt(0)
	s_waitcnt vmcnt(13)
	s_waitcnt lgkmcnt(0)
	v_lshlrev_b32_e32 v240, 16, v184
	v_and_b32_e32 v241, 0xffff0000, v184
	v_pk_mul_f32 v[64:65], v[64:65], v[240:241]
	v_lshlrev_b32_e32 v244, 16, v185
	v_and_b32_e32 v245, 0xffff0000, v185
	v_pk_mul_f32 v[66:67], v[66:67], v[244:245]
	v_lshlrev_b32_e32 v246, 16, v186
	v_and_b32_e32 v247, 0xffff0000, v186
	v_pk_mul_f32 v[68:69], v[68:69], v[246:247]
	v_lshlrev_b32_e32 v252, 16, v187
	v_and_b32_e32 v253, 0xffff0000, v187
	v_pk_mul_f32 v[70:71], v[70:71], v[252:253]
	v_lshlrev_b32_e32 v178, 16, v192
	v_and_b32_e32 v179, 0xffff0000, v192
	v_pk_add_f32 v[64:65], v[64:65], v[178:179]
	v_lshlrev_b32_e32 v240, 16, v193
	v_and_b32_e32 v241, 0xffff0000, v193
	v_pk_add_f32 v[66:67], v[66:67], v[240:241]
	v_lshlrev_b32_e32 v244, 16, v194
	v_and_b32_e32 v245, 0xffff0000, v194
	v_pk_add_f32 v[68:69], v[68:69], v[244:245]
	v_lshlrev_b32_e32 v246, 16, v195
	v_and_b32_e32 v247, 0xffff0000, v195
	v_pk_add_f32 v[70:71], v[70:71], v[246:247]
	v_cvt_pk_bf16_f32 v184, v64, v65
	v_cvt_pk_bf16_f32 v185, v66, v67
	v_cvt_pk_bf16_f32 v186, v68, v69
	v_cvt_pk_bf16_f32 v187, v70, v71
	ds_write_b128 v177, v[184:187] offset:8192
	s_waitcnt lgkmcnt(0)
	s_waitcnt vmcnt(12)
	s_waitcnt lgkmcnt(0)
	v_lshlrev_b32_e32 v252, 16, v188
	v_and_b32_e32 v253, 0xffff0000, v188
	v_pk_mul_f32 v[72:73], v[72:73], v[252:253]
	v_lshlrev_b32_e32 v178, 16, v189
	v_and_b32_e32 v179, 0xffff0000, v189
	v_pk_mul_f32 v[74:75], v[74:75], v[178:179]
	v_lshlrev_b32_e32 v240, 16, v190
	v_and_b32_e32 v241, 0xffff0000, v190
	v_pk_mul_f32 v[76:77], v[76:77], v[240:241]
	v_lshlrev_b32_e32 v244, 16, v191
	v_and_b32_e32 v245, 0xffff0000, v191
	v_pk_mul_f32 v[78:79], v[78:79], v[244:245]
	v_lshlrev_b32_e32 v246, 16, v196
	v_and_b32_e32 v247, 0xffff0000, v196
	v_pk_add_f32 v[72:73], v[72:73], v[246:247]
	v_lshlrev_b32_e32 v252, 16, v197
	v_and_b32_e32 v253, 0xffff0000, v197
	v_pk_add_f32 v[74:75], v[74:75], v[252:253]
	v_lshlrev_b32_e32 v178, 16, v198
	v_and_b32_e32 v179, 0xffff0000, v198
	v_pk_add_f32 v[76:77], v[76:77], v[178:179]
	v_lshlrev_b32_e32 v240, 16, v199
	v_and_b32_e32 v241, 0xffff0000, v199
	v_pk_add_f32 v[78:79], v[78:79], v[240:241]
	v_cvt_pk_bf16_f32 v188, v72, v73
	v_cvt_pk_bf16_f32 v189, v74, v75
	v_cvt_pk_bf16_f32 v190, v76, v77
	v_cvt_pk_bf16_f32 v191, v78, v79
	ds_write_b128 v177, v[188:191] offset:16384
	s_waitcnt lgkmcnt(0)
	s_waitcnt vmcnt(9)
	v_lshlrev_b32_e32 v244, 16, v236
	v_and_b32_e32 v245, 0xffff0000, v236
	v_pk_mul_f32 v[80:81], v[80:81], v[244:245]
	v_lshlrev_b32_e32 v246, 16, v237
	v_and_b32_e32 v247, 0xffff0000, v237
	v_pk_mul_f32 v[82:83], v[82:83], v[246:247]
	v_lshlrev_b32_e32 v252, 16, v238
	v_and_b32_e32 v253, 0xffff0000, v238
	v_pk_mul_f32 v[84:85], v[84:85], v[252:253]
	v_lshlrev_b32_e32 v178, 16, v239
	v_and_b32_e32 v179, 0xffff0000, v239
	v_pk_mul_f32 v[86:87], v[86:87], v[178:179]
	v_lshlrev_b32_e32 v240, 16, v4
	v_and_b32_e32 v241, 0xffff0000, v4
	v_pk_add_f32 v[80:81], v[80:81], v[240:241]
	v_lshlrev_b32_e32 v244, 16, v5
	v_and_b32_e32 v245, 0xffff0000, v5
	v_pk_add_f32 v[82:83], v[82:83], v[244:245]
	v_lshlrev_b32_e32 v246, 16, v6
	v_and_b32_e32 v247, 0xffff0000, v6
	v_pk_add_f32 v[84:85], v[84:85], v[246:247]
	v_lshlrev_b32_e32 v252, 16, v7
	v_and_b32_e32 v253, 0xffff0000, v7
	v_pk_add_f32 v[86:87], v[86:87], v[252:253]
	v_cvt_pk_bf16_f32 v236, v80, v81
	v_cvt_pk_bf16_f32 v237, v82, v83
	v_cvt_pk_bf16_f32 v238, v84, v85
	v_cvt_pk_bf16_f32 v239, v86, v87
	s_mov_b32 s58, 0x48000
	v_lshl_add_u64 v[178:179], v[172:173], 0, s[58:59]
	global_store_dwordx4 v[178:179], v[236:239], off
	s_waitcnt vmcnt(9)
	v_lshlrev_b32_e32 v240, 16, v0
	v_and_b32_e32 v241, 0xffff0000, v0
	v_pk_mul_f32 v[88:89], v[88:89], v[240:241]
	v_lshlrev_b32_e32 v244, 16, v1
	v_and_b32_e32 v245, 0xffff0000, v1
	v_pk_mul_f32 v[90:91], v[90:91], v[244:245]
	v_lshlrev_b32_e32 v246, 16, v2
	v_and_b32_e32 v247, 0xffff0000, v2
	v_pk_mul_f32 v[92:93], v[92:93], v[246:247]
	v_lshlrev_b32_e32 v252, 16, v3
	v_and_b32_e32 v253, 0xffff0000, v3
	v_pk_mul_f32 v[94:95], v[94:95], v[252:253]
	v_lshlrev_b32_e32 v178, 16, v128
	v_and_b32_e32 v179, 0xffff0000, v128
	v_pk_add_f32 v[88:89], v[88:89], v[178:179]
	v_lshlrev_b32_e32 v240, 16, v129
	v_and_b32_e32 v241, 0xffff0000, v129
	v_pk_add_f32 v[90:91], v[90:91], v[240:241]
	v_lshlrev_b32_e32 v244, 16, v130
	v_and_b32_e32 v245, 0xffff0000, v130
	v_pk_add_f32 v[92:93], v[92:93], v[244:245]
	v_lshlrev_b32_e32 v246, 16, v131
	v_and_b32_e32 v247, 0xffff0000, v131
	v_pk_add_f32 v[94:95], v[94:95], v[246:247]
	v_cvt_pk_bf16_f32 v0, v88, v89
	v_cvt_pk_bf16_f32 v1, v90, v91
	v_cvt_pk_bf16_f32 v2, v92, v93
	v_cvt_pk_bf16_f32 v3, v94, v95
	s_mov_b32 s58, 0x48000
	v_lshl_add_u64 v[252:253], v[172:173], 0, s[58:59]
	global_store_dwordx4 v[252:253], v[0:3], off offset:256
	s_waitcnt vmcnt(7)
	v_lshlrev_b32_e32 v178, 16, v8
	v_and_b32_e32 v179, 0xffff0000, v8
	v_pk_mul_f32 v[96:97], v[96:97], v[178:179]
	v_lshlrev_b32_e32 v240, 16, v9
	v_and_b32_e32 v241, 0xffff0000, v9
	v_pk_mul_f32 v[98:99], v[98:99], v[240:241]
	v_lshlrev_b32_e32 v244, 16, v10
	v_and_b32_e32 v245, 0xffff0000, v10
	v_pk_mul_f32 v[100:101], v[100:101], v[244:245]
	v_lshlrev_b32_e32 v246, 16, v11
	v_and_b32_e32 v247, 0xffff0000, v11
	v_pk_mul_f32 v[102:103], v[102:103], v[246:247]
	v_lshlrev_b32_e32 v252, 16, v132
	v_and_b32_e32 v253, 0xffff0000, v132
	v_pk_add_f32 v[96:97], v[96:97], v[252:253]
	v_lshlrev_b32_e32 v178, 16, v133
	v_and_b32_e32 v179, 0xffff0000, v133
	v_pk_add_f32 v[98:99], v[98:99], v[178:179]
	v_lshlrev_b32_e32 v240, 16, v134
	v_and_b32_e32 v241, 0xffff0000, v134
	v_pk_add_f32 v[100:101], v[100:101], v[240:241]
	v_lshlrev_b32_e32 v244, 16, v135
	v_and_b32_e32 v245, 0xffff0000, v135
	v_pk_add_f32 v[102:103], v[102:103], v[244:245]
	v_cvt_pk_bf16_f32 v8, v96, v97
	v_cvt_pk_bf16_f32 v9, v98, v99
	v_cvt_pk_bf16_f32 v10, v100, v101
	v_cvt_pk_bf16_f32 v11, v102, v103
	s_mov_b32 s58, 0x50000
	v_lshl_add_u64 v[246:247], v[172:173], 0, s[58:59]
	global_store_dwordx4 v[246:247], v[8:11], off
	s_waitcnt vmcnt(7)
	v_lshlrev_b32_e32 v252, 16, v12
	v_and_b32_e32 v253, 0xffff0000, v12
	v_pk_mul_f32 v[104:105], v[104:105], v[252:253]
	v_lshlrev_b32_e32 v178, 16, v13
	v_and_b32_e32 v179, 0xffff0000, v13
	v_pk_mul_f32 v[106:107], v[106:107], v[178:179]
	v_lshlrev_b32_e32 v240, 16, v14
	v_and_b32_e32 v241, 0xffff0000, v14
	v_pk_mul_f32 v[108:109], v[108:109], v[240:241]
	v_lshlrev_b32_e32 v244, 16, v15
	v_and_b32_e32 v245, 0xffff0000, v15
	v_pk_mul_f32 v[110:111], v[110:111], v[244:245]
	v_lshlrev_b32_e32 v246, 16, v16
	v_and_b32_e32 v247, 0xffff0000, v16
	v_pk_add_f32 v[104:105], v[104:105], v[246:247]
	v_lshlrev_b32_e32 v252, 16, v17
	v_and_b32_e32 v253, 0xffff0000, v17
	v_pk_add_f32 v[106:107], v[106:107], v[252:253]
	v_lshlrev_b32_e32 v178, 16, v18
	v_and_b32_e32 v179, 0xffff0000, v18
	v_pk_add_f32 v[108:109], v[108:109], v[178:179]
	v_lshlrev_b32_e32 v240, 16, v19
	v_and_b32_e32 v241, 0xffff0000, v19
	v_pk_add_f32 v[110:111], v[110:111], v[240:241]
	v_cvt_pk_bf16_f32 v12, v104, v105
	v_cvt_pk_bf16_f32 v13, v106, v107
	v_cvt_pk_bf16_f32 v14, v108, v109
	v_cvt_pk_bf16_f32 v15, v110, v111
	s_mov_b32 s58, 0x50000
	v_lshl_add_u64 v[244:245], v[172:173], 0, s[58:59]
	global_store_dwordx4 v[244:245], v[12:15], off offset:256
	s_waitcnt vmcnt(5)
	v_lshlrev_b32_e32 v246, 16, v20
	v_and_b32_e32 v247, 0xffff0000, v20
	v_pk_mul_f32 v[112:113], v[112:113], v[246:247]
	v_lshlrev_b32_e32 v252, 16, v21
	v_and_b32_e32 v253, 0xffff0000, v21
	v_pk_mul_f32 v[114:115], v[114:115], v[252:253]
	v_lshlrev_b32_e32 v178, 16, v22
	v_and_b32_e32 v179, 0xffff0000, v22
	v_pk_mul_f32 v[116:117], v[116:117], v[178:179]
	v_lshlrev_b32_e32 v240, 16, v23
	v_and_b32_e32 v241, 0xffff0000, v23
	v_pk_mul_f32 v[118:119], v[118:119], v[240:241]
	v_lshlrev_b32_e32 v244, 16, v24
	v_and_b32_e32 v245, 0xffff0000, v24
	v_pk_add_f32 v[112:113], v[112:113], v[244:245]
	v_lshlrev_b32_e32 v246, 16, v25
	v_and_b32_e32 v247, 0xffff0000, v25
	v_pk_add_f32 v[114:115], v[114:115], v[246:247]
	v_lshlrev_b32_e32 v252, 16, v26
	v_and_b32_e32 v253, 0xffff0000, v26
	v_pk_add_f32 v[116:117], v[116:117], v[252:253]
	v_lshlrev_b32_e32 v178, 16, v27
	v_and_b32_e32 v179, 0xffff0000, v27
	v_pk_add_f32 v[118:119], v[118:119], v[178:179]
	v_cvt_pk_bf16_f32 v20, v112, v113
	v_cvt_pk_bf16_f32 v21, v114, v115
	v_cvt_pk_bf16_f32 v22, v116, v117
	v_cvt_pk_bf16_f32 v23, v118, v119
	s_mov_b32 s58, 0x58000
	v_lshl_add_u64 v[240:241], v[172:173], 0, s[58:59]
	global_store_dwordx4 v[240:241], v[20:23], off
	s_waitcnt vmcnt(5)
	v_lshlrev_b32_e32 v244, 16, v136
	v_and_b32_e32 v245, 0xffff0000, v136
	v_pk_mul_f32 v[120:121], v[120:121], v[244:245]
	v_lshlrev_b32_e32 v246, 16, v137
	v_and_b32_e32 v247, 0xffff0000, v137
	v_pk_mul_f32 v[122:123], v[122:123], v[246:247]
	v_lshlrev_b32_e32 v252, 16, v138
	v_and_b32_e32 v253, 0xffff0000, v138
	v_pk_mul_f32 v[124:125], v[124:125], v[252:253]
	v_lshlrev_b32_e32 v178, 16, v139
	v_and_b32_e32 v179, 0xffff0000, v139
	v_pk_mul_f32 v[126:127], v[126:127], v[178:179]
	v_lshlrev_b32_e32 v240, 16, v28
	v_and_b32_e32 v241, 0xffff0000, v28
	v_pk_add_f32 v[120:121], v[120:121], v[240:241]
	v_lshlrev_b32_e32 v244, 16, v29
	v_and_b32_e32 v245, 0xffff0000, v29
	v_pk_add_f32 v[122:123], v[122:123], v[244:245]
	v_lshlrev_b32_e32 v246, 16, v30
	v_and_b32_e32 v247, 0xffff0000, v30
	v_pk_add_f32 v[124:125], v[124:125], v[246:247]
	v_lshlrev_b32_e32 v252, 16, v31
	v_and_b32_e32 v253, 0xffff0000, v31
	v_pk_add_f32 v[126:127], v[126:127], v[252:253]
	v_cvt_pk_bf16_f32 v136, v120, v121
	v_cvt_pk_bf16_f32 v137, v122, v123
	v_cvt_pk_bf16_f32 v138, v124, v125
	v_cvt_pk_bf16_f32 v139, v126, v127
	s_mov_b32 s58, 0x58000
	v_lshl_add_u64 v[178:179], v[172:173], 0, s[58:59]
	global_store_dwordx4 v[178:179], v[136:139], off offset:256
	s_branch .Lmepi_done
.Lmepi_z3:
	global_load_dwordx4 v[128:131], v[170:171], off nt
	global_load_dwordx4 v[132:135], v[170:171], off offset:256 nt
	s_mov_b32 s58, 0x20000
	v_lshl_add_u64 v[244:245], v[170:171], 0, s[58:59]
	global_load_dwordx4 v[136:139], v[244:245], off nt
	global_load_dwordx4 v[140:143], v[244:245], off offset:256 nt
	s_mov_b32 s58, 0x40000
	v_lshl_add_u64 v[246:247], v[170:171], 0, s[58:59]
	global_load_dwordx4 v[144:147], v[246:247], off nt
	global_load_dwordx4 v[148:151], v[246:247], off offset:256 nt
	s_mov_b32 s58, 0x60000
	v_lshl_add_u64 v[252:253], v[170:171], 0, s[58:59]
	global_load_dwordx4 v[152:155], v[252:253], off nt
	global_load_dwordx4 v[156:159], v[252:253], off offset:256 nt
	ds_read_b128 v[180:183], v177 offset:0
	s_mov_b32 s58, 0x100000
	v_lshl_add_u64 v[178:179], v[170:171], 0, s[58:59]
	global_load_dwordx4 v[184:187], v[178:179], off nt
	global_load_dwordx4 v[188:191], v[178:179], off offset:256 nt
	ds_read_b128 v[192:195], v177 offset:8192
	ds_read_b128 v[196:199], v177 offset:16384
	s_waitcnt vmcnt(9)
	v_lshlrev_b32_e32 v240, 16, v128
	v_and_b32_e32 v241, 0xffff0000, v128
	v_pk_mul_f32 v[0:1], v[0:1], v[240:241]
	v_lshlrev_b32_e32 v244, 16, v129
	v_and_b32_e32 v245, 0xffff0000, v129
	v_pk_mul_f32 v[2:3], v[2:3], v[244:245]
	v_lshlrev_b32_e32 v246, 16, v130
	v_and_b32_e32 v247, 0xffff0000, v130
	v_pk_mul_f32 v[4:5], v[4:5], v[246:247]
	v_lshlrev_b32_e32 v252, 16, v131
	v_and_b32_e32 v253, 0xffff0000, v131
	v_pk_mul_f32 v[6:7], v[6:7], v[252:253]
	v_lshlrev_b32_e32 v178, 16, v200
	v_and_b32_e32 v179, 0xffff0000, v200
	v_pk_add_f32 v[0:1], v[0:1], v[178:179]
	v_lshlrev_b32_e32 v240, 16, v201
	v_and_b32_e32 v241, 0xffff0000, v201
	v_pk_add_f32 v[2:3], v[2:3], v[240:241]
	v_lshlrev_b32_e32 v244, 16, v202
	v_and_b32_e32 v245, 0xffff0000, v202
	v_pk_add_f32 v[4:5], v[4:5], v[244:245]
	v_lshlrev_b32_e32 v246, 16, v203
	v_and_b32_e32 v247, 0xffff0000, v203
	v_pk_add_f32 v[6:7], v[6:7], v[246:247]
	v_cvt_pk_bf16_f32 v128, v0, v1
	v_cvt_pk_bf16_f32 v129, v2, v3
	v_cvt_pk_bf16_f32 v130, v4, v5
	v_cvt_pk_bf16_f32 v131, v6, v7
	global_store_dwordx4 v[172:173], v[128:131], off sc1
	s_waitcnt vmcnt(9)
	v_lshlrev_b32_e32 v252, 16, v132
	v_and_b32_e32 v253, 0xffff0000, v132
	v_pk_mul_f32 v[8:9], v[8:9], v[252:253]
	v_lshlrev_b32_e32 v178, 16, v133
	v_and_b32_e32 v179, 0xffff0000, v133
	v_pk_mul_f32 v[10:11], v[10:11], v[178:179]
	v_lshlrev_b32_e32 v240, 16, v134
	v_and_b32_e32 v241, 0xffff0000, v134
	v_pk_mul_f32 v[12:13], v[12:13], v[240:241]
	v_lshlrev_b32_e32 v244, 16, v135
	v_and_b32_e32 v245, 0xffff0000, v135
	v_pk_mul_f32 v[14:15], v[14:15], v[244:245]
	v_lshlrev_b32_e32 v246, 16, v204
	v_and_b32_e32 v247, 0xffff0000, v204
	v_pk_add_f32 v[8:9], v[8:9], v[246:247]
	v_lshlrev_b32_e32 v252, 16, v205
	v_and_b32_e32 v253, 0xffff0000, v205
	v_pk_add_f32 v[10:11], v[10:11], v[252:253]
	v_lshlrev_b32_e32 v178, 16, v206
	v_and_b32_e32 v179, 0xffff0000, v206
	v_pk_add_f32 v[12:13], v[12:13], v[178:179]
	v_lshlrev_b32_e32 v240, 16, v207
	v_and_b32_e32 v241, 0xffff0000, v207
	v_pk_add_f32 v[14:15], v[14:15], v[240:241]
	v_cvt_pk_bf16_f32 v132, v8, v9
	v_cvt_pk_bf16_f32 v133, v10, v11
	v_cvt_pk_bf16_f32 v134, v12, v13
	v_cvt_pk_bf16_f32 v135, v14, v15
	global_store_dwordx4 v[172:173], v[132:135], off offset:256 sc1
	s_mov_b32 s58, 0x120000
	v_lshl_add_u64 v[244:245], v[170:171], 0, s[58:59]
	global_load_dwordx4 v[236:239], v[244:245], off nt
	global_load_dwordx4 v[0:3], v[244:245], off offset:256 nt
	s_mov_b32 s58, 0x48000
	v_lshl_add_u64 v[246:247], v[172:173], 0, s[58:59]
	global_load_dwordx4 v[4:7], v[246:247], off
	global_load_dwordx4 v[128:131], v[246:247], off offset:256
	s_waitcnt vmcnt(13)
	v_lshlrev_b32_e32 v252, 16, v136
	v_and_b32_e32 v253, 0xffff0000, v136
	v_pk_mul_f32 v[16:17], v[16:17], v[252:253]
	v_lshlrev_b32_e32 v178, 16, v137
	v_and_b32_e32 v179, 0xffff0000, v137
	v_pk_mul_f32 v[18:19], v[18:19], v[178:179]
	v_lshlrev_b32_e32 v240, 16, v138
	v_and_b32_e32 v241, 0xffff0000, v138
	v_pk_mul_f32 v[20:21], v[20:21], v[240:241]
	v_lshlrev_b32_e32 v244, 16, v139
	v_and_b32_e32 v245, 0xffff0000, v139
	v_pk_mul_f32 v[22:23], v[22:23], v[244:245]
	v_lshlrev_b32_e32 v246, 16, v208
	v_and_b32_e32 v247, 0xffff0000, v208
	v_pk_add_f32 v[16:17], v[16:17], v[246:247]
	v_lshlrev_b32_e32 v252, 16, v209
	v_and_b32_e32 v253, 0xffff0000, v209
	v_pk_add_f32 v[18:19], v[18:19], v[252:253]
	v_lshlrev_b32_e32 v178, 16, v210
	v_and_b32_e32 v179, 0xffff0000, v210
	v_pk_add_f32 v[20:21], v[20:21], v[178:179]
	v_lshlrev_b32_e32 v240, 16, v211
	v_and_b32_e32 v241, 0xffff0000, v211
	v_pk_add_f32 v[22:23], v[22:23], v[240:241]
	v_cvt_pk_bf16_f32 v136, v16, v17
	v_cvt_pk_bf16_f32 v137, v18, v19
	v_cvt_pk_bf16_f32 v138, v20, v21
	v_cvt_pk_bf16_f32 v139, v22, v23
	s_mov_b32 s58, 0x8000
	v_lshl_add_u64 v[244:245], v[172:173], 0, s[58:59]
	global_store_dwordx4 v[244:245], v[136:139], off sc1
	s_waitcnt vmcnt(13)
	v_lshlrev_b32_e32 v246, 16, v140
	v_and_b32_e32 v247, 0xffff0000, v140
	v_pk_mul_f32 v[24:25], v[24:25], v[246:247]
	v_lshlrev_b32_e32 v252, 16, v141
	v_and_b32_e32 v253, 0xffff0000, v141
	v_pk_mul_f32 v[26:27], v[26:27], v[252:253]
	v_lshlrev_b32_e32 v178, 16, v142
	v_and_b32_e32 v179, 0xffff0000, v142
	v_pk_mul_f32 v[28:29], v[28:29], v[178:179]
	v_lshlrev_b32_e32 v240, 16, v143
	v_and_b32_e32 v241, 0xffff0000, v143
	v_pk_mul_f32 v[30:31], v[30:31], v[240:241]
	v_lshlrev_b32_e32 v244, 16, v212
	v_and_b32_e32 v245, 0xffff0000, v212
	v_pk_add_f32 v[24:25], v[24:25], v[244:245]
	v_lshlrev_b32_e32 v246, 16, v213
	v_and_b32_e32 v247, 0xffff0000, v213
	v_pk_add_f32 v[26:27], v[26:27], v[246:247]
	v_lshlrev_b32_e32 v252, 16, v214
	v_and_b32_e32 v253, 0xffff0000, v214
	v_pk_add_f32 v[28:29], v[28:29], v[252:253]
	v_lshlrev_b32_e32 v178, 16, v215
	v_and_b32_e32 v179, 0xffff0000, v215
	v_pk_add_f32 v[30:31], v[30:31], v[178:179]
	v_cvt_pk_bf16_f32 v140, v24, v25
	v_cvt_pk_bf16_f32 v141, v26, v27
	v_cvt_pk_bf16_f32 v142, v28, v29
	v_cvt_pk_bf16_f32 v143, v30, v31
	s_mov_b32 s58, 0x8000
	v_lshl_add_u64 v[240:241], v[172:173], 0, s[58:59]
	global_store_dwordx4 v[240:241], v[140:143], off offset:256 sc1
	s_mov_b32 s58, 0x140000
	v_lshl_add_u64 v[244:245], v[170:171], 0, s[58:59]
	global_load_dwordx4 v[8:11], v[244:245], off nt
	global_load_dwordx4 v[12:15], v[244:245], off offset:256 nt
	s_mov_b32 s58, 0x50000
	v_lshl_add_u64 v[246:247], v[172:173], 0, s[58:59]
	global_load_dwordx4 v[132:135], v[246:247], off
	global_load_dwordx4 v[16:19], v[246:247], off offset:256
	s_mov_b32 s58, 0x160000
	v_lshl_add_u64 v[252:253], v[170:171], 0, s[58:59]
	global_load_dwordx4 v[20:23], v[252:253], off nt
	global_load_dwordx4 v[136:139], v[252:253], off offset:256 nt
	s_mov_b32 s58, 0x58000
	v_lshl_add_u64 v[178:179], v[172:173], 0, s[58:59]
	global_load_dwordx4 v[24:27], v[178:179], off
	global_load_dwordx4 v[28:31], v[178:179], off offset:256
	s_waitcnt vmcnt(21)
	v_lshlrev_b32_e32 v240, 16, v144
	v_and_b32_e32 v241, 0xffff0000, v144
	v_pk_mul_f32 v[32:33], v[32:33], v[240:241]
	v_lshlrev_b32_e32 v244, 16, v145
	v_and_b32_e32 v245, 0xffff0000, v145
	v_pk_mul_f32 v[34:35], v[34:35], v[244:245]
	v_lshlrev_b32_e32 v246, 16, v146
	v_and_b32_e32 v247, 0xffff0000, v146
	v_pk_mul_f32 v[36:37], v[36:37], v[246:247]
	v_lshlrev_b32_e32 v252, 16, v147
	v_and_b32_e32 v253, 0xffff0000, v147
	v_pk_mul_f32 v[38:39], v[38:39], v[252:253]
	v_lshlrev_b32_e32 v178, 16, v216
	v_and_b32_e32 v179, 0xffff0000, v216
	v_pk_add_f32 v[32:33], v[32:33], v[178:179]
	v_lshlrev_b32_e32 v240, 16, v217
	v_and_b32_e32 v241, 0xffff0000, v217
	v_pk_add_f32 v[34:35], v[34:35], v[240:241]
	v_lshlrev_b32_e32 v244, 16, v218
	v_and_b32_e32 v245, 0xffff0000, v218
	v_pk_add_f32 v[36:37], v[36:37], v[244:245]
	v_lshlrev_b32_e32 v246, 16, v219
	v_and_b32_e32 v247, 0xffff0000, v219
	v_pk_add_f32 v[38:39], v[38:39], v[246:247]
	v_cvt_pk_bf16_f32 v144, v32, v33
	v_cvt_pk_bf16_f32 v145, v34, v35
	v_cvt_pk_bf16_f32 v146, v36, v37
	v_cvt_pk_bf16_f32 v147, v38, v39
	s_mov_b32 s58, 0x10000
	v_lshl_add_u64 v[252:253], v[172:173], 0, s[58:59]
	global_store_dwordx4 v[252:253], v[144:147], off sc1
	s_waitcnt vmcnt(21)
	v_lshlrev_b32_e32 v178, 16, v148
	v_and_b32_e32 v179, 0xffff0000, v148
	v_pk_mul_f32 v[40:41], v[40:41], v[178:179]
	v_lshlrev_b32_e32 v240, 16, v149
	v_and_b32_e32 v241, 0xffff0000, v149
	v_pk_mul_f32 v[42:43], v[42:43], v[240:241]
	v_lshlrev_b32_e32 v244, 16, v150
	v_and_b32_e32 v245, 0xffff0000, v150
	v_pk_mul_f32 v[44:45], v[44:45], v[244:245]
	v_lshlrev_b32_e32 v246, 16, v151
	v_and_b32_e32 v247, 0xffff0000, v151
	v_pk_mul_f32 v[46:47], v[46:47], v[246:247]
	v_lshlrev_b32_e32 v252, 16, v220
	v_and_b32_e32 v253, 0xffff0000, v220
	v_pk_add_f32 v[40:41], v[40:41], v[252:253]
	v_lshlrev_b32_e32 v178, 16, v221
	v_and_b32_e32 v179, 0xffff0000, v221
	v_pk_add_f32 v[42:43], v[42:43], v[178:179]
	v_lshlrev_b32_e32 v240, 16, v222
	v_and_b32_e32 v241, 0xffff0000, v222
	v_pk_add_f32 v[44:45], v[44:45], v[240:241]
	v_lshlrev_b32_e32 v244, 16, v223
	v_and_b32_e32 v245, 0xffff0000, v223
	v_pk_add_f32 v[46:47], v[46:47], v[244:245]
	v_cvt_pk_bf16_f32 v148, v40, v41
	v_cvt_pk_bf16_f32 v149, v42, v43
	v_cvt_pk_bf16_f32 v150, v44, v45
	v_cvt_pk_bf16_f32 v151, v46, v47
	s_mov_b32 s58, 0x10000
	v_lshl_add_u64 v[246:247], v[172:173], 0, s[58:59]
	global_store_dwordx4 v[246:247], v[148:151], off offset:256 sc1
	s_waitcnt vmcnt(21)
	v_lshlrev_b32_e32 v252, 16, v152
	v_and_b32_e32 v253, 0xffff0000, v152
	v_pk_mul_f32 v[48:49], v[48:49], v[252:253]
	v_lshlrev_b32_e32 v178, 16, v153
	v_and_b32_e32 v179, 0xffff0000, v153
	v_pk_mul_f32 v[50:51], v[50:51], v[178:179]
	v_lshlrev_b32_e32 v240, 16, v154
	v_and_b32_e32 v241, 0xffff0000, v154
	v_pk_mul_f32 v[52:53], v[52:53], v[240:241]
	v_lshlrev_b32_e32 v244, 16, v155
	v_and_b32_e32 v245, 0xffff0000, v155
	v_pk_mul_f32 v[54:55], v[54:55], v[244:245]
	v_lshlrev_b32_e32 v246, 16, v224
	v_and_b32_e32 v247, 0xffff0000, v224
	v_pk_add_f32 v[48:49], v[48:49], v[246:247]
	v_lshlrev_b32_e32 v252, 16, v225
	v_and_b32_e32 v253, 0xffff0000, v225
	v_pk_add_f32 v[50:51], v[50:51], v[252:253]
	v_lshlrev_b32_e32 v178, 16, v226
	v_and_b32_e32 v179, 0xffff0000, v226
	v_pk_add_f32 v[52:53], v[52:53], v[178:179]
	v_lshlrev_b32_e32 v240, 16, v227
	v_and_b32_e32 v241, 0xffff0000, v227
	v_pk_add_f32 v[54:55], v[54:55], v[240:241]
	v_cvt_pk_bf16_f32 v152, v48, v49
	v_cvt_pk_bf16_f32 v153, v50, v51
	v_cvt_pk_bf16_f32 v154, v52, v53
	v_cvt_pk_bf16_f32 v155, v54, v55
	s_mov_b32 s58, 0x18000
	v_lshl_add_u64 v[244:245], v[172:173], 0, s[58:59]
	global_store_dwordx4 v[244:245], v[152:155], off sc1
	s_waitcnt vmcnt(21)
	s_waitcnt lgkmcnt(0)
	v_lshlrev_b32_e32 v246, 16, v156
	v_and_b32_e32 v247, 0xffff0000, v156
	v_pk_mul_f32 v[56:57], v[56:57], v[246:247]
	v_lshlrev_b32_e32 v252, 16, v157
	v_and_b32_e32 v253, 0xffff0000, v157
	v_pk_mul_f32 v[58:59], v[58:59], v[252:253]
	v_lshlrev_b32_e32 v178, 16, v158
	v_and_b32_e32 v179, 0xffff0000, v158
	v_pk_mul_f32 v[60:61], v[60:61], v[178:179]
	v_lshlrev_b32_e32 v240, 16, v159
	v_and_b32_e32 v241, 0xffff0000, v159
	v_pk_mul_f32 v[62:63], v[62:63], v[240:241]
	v_lshlrev_b32_e32 v244, 16, v180
	v_and_b32_e32 v245, 0xffff0000, v180
	v_pk_add_f32 v[56:57], v[56:57], v[244:245]
	v_lshlrev_b32_e32 v246, 16, v181
	v_and_b32_e32 v247, 0xffff0000, v181
	v_pk_add_f32 v[58:59], v[58:59], v[246:247]
	v_lshlrev_b32_e32 v252, 16, v182
	v_and_b32_e32 v253, 0xffff0000, v182
	v_pk_add_f32 v[60:61], v[60:61], v[252:253]
	v_lshlrev_b32_e32 v178, 16, v183
	v_and_b32_e32 v179, 0xffff0000, v183
	v_pk_add_f32 v[62:63], v[62:63], v[178:179]
	v_cvt_pk_bf16_f32 v156, v56, v57
	v_cvt_pk_bf16_f32 v157, v58, v59
	v_cvt_pk_bf16_f32 v158, v60, v61
	v_cvt_pk_bf16_f32 v159, v62, v63
	s_mov_b32 s58, 0x18000
	v_lshl_add_u64 v[240:241], v[172:173], 0, s[58:59]
	global_store_dwordx4 v[240:241], v[156:159], off offset:256 sc1
	s_waitcnt vmcnt(21)
	s_waitcnt lgkmcnt(0)
	v_lshlrev_b32_e32 v244, 16, v184
	v_and_b32_e32 v245, 0xffff0000, v184
	v_pk_mul_f32 v[64:65], v[64:65], v[244:245]
	v_lshlrev_b32_e32 v246, 16, v185
	v_and_b32_e32 v247, 0xffff0000, v185
	v_pk_mul_f32 v[66:67], v[66:67], v[246:247]
	v_lshlrev_b32_e32 v252, 16, v186
	v_and_b32_e32 v253, 0xffff0000, v186
	v_pk_mul_f32 v[68:69], v[68:69], v[252:253]
	v_lshlrev_b32_e32 v178, 16, v187
	v_and_b32_e32 v179, 0xffff0000, v187
	v_pk_mul_f32 v[70:71], v[70:71], v[178:179]
	v_lshlrev_b32_e32 v240, 16, v192
	v_and_b32_e32 v241, 0xffff0000, v192
	v_pk_add_f32 v[64:65], v[64:65], v[240:241]
	v_lshlrev_b32_e32 v244, 16, v193
	v_and_b32_e32 v245, 0xffff0000, v193
	v_pk_add_f32 v[66:67], v[66:67], v[244:245]
	v_lshlrev_b32_e32 v246, 16, v194
	v_and_b32_e32 v247, 0xffff0000, v194
	v_pk_add_f32 v[68:69], v[68:69], v[246:247]
	v_lshlrev_b32_e32 v252, 16, v195
	v_and_b32_e32 v253, 0xffff0000, v195
	v_pk_add_f32 v[70:71], v[70:71], v[252:253]
	v_cvt_pk_bf16_f32 v184, v64, v65
	v_cvt_pk_bf16_f32 v185, v66, v67
	v_cvt_pk_bf16_f32 v186, v68, v69
	v_cvt_pk_bf16_f32 v187, v70, v71
	s_mov_b32 s58, 0x40000
	v_lshl_add_u64 v[178:179], v[172:173], 0, s[58:59]
	global_store_dwordx4 v[178:179], v[184:187], off sc1
	s_waitcnt vmcnt(21)
	s_waitcnt lgkmcnt(0)
	v_lshlrev_b32_e32 v240, 16, v188
	v_and_b32_e32 v241, 0xffff0000, v188
	v_pk_mul_f32 v[72:73], v[72:73], v[240:241]
	v_lshlrev_b32_e32 v244, 16, v189
	v_and_b32_e32 v245, 0xffff0000, v189
	v_pk_mul_f32 v[74:75], v[74:75], v[244:245]
	v_lshlrev_b32_e32 v246, 16, v190
	v_and_b32_e32 v247, 0xffff0000, v190
	v_pk_mul_f32 v[76:77], v[76:77], v[246:247]
	v_lshlrev_b32_e32 v252, 16, v191
	v_and_b32_e32 v253, 0xffff0000, v191
	v_pk_mul_f32 v[78:79], v[78:79], v[252:253]
	v_lshlrev_b32_e32 v178, 16, v196
	v_and_b32_e32 v179, 0xffff0000, v196
	v_pk_add_f32 v[72:73], v[72:73], v[178:179]
	v_lshlrev_b32_e32 v240, 16, v197
	v_and_b32_e32 v241, 0xffff0000, v197
	v_pk_add_f32 v[74:75], v[74:75], v[240:241]
	v_lshlrev_b32_e32 v244, 16, v198
	v_and_b32_e32 v245, 0xffff0000, v198
	v_pk_add_f32 v[76:77], v[76:77], v[244:245]
	v_lshlrev_b32_e32 v246, 16, v199
	v_and_b32_e32 v247, 0xffff0000, v199
	v_pk_add_f32 v[78:79], v[78:79], v[246:247]
	v_cvt_pk_bf16_f32 v188, v72, v73
	v_cvt_pk_bf16_f32 v189, v74, v75
	v_cvt_pk_bf16_f32 v190, v76, v77
	v_cvt_pk_bf16_f32 v191, v78, v79
	s_mov_b32 s58, 0x40000
	v_lshl_add_u64 v[252:253], v[172:173], 0, s[58:59]
	global_store_dwordx4 v[252:253], v[188:191], off offset:256 sc1
	s_waitcnt vmcnt(17)
	v_lshlrev_b32_e32 v178, 16, v236
	v_and_b32_e32 v179, 0xffff0000, v236
	v_pk_mul_f32 v[80:81], v[80:81], v[178:179]
	v_lshlrev_b32_e32 v240, 16, v237
	v_and_b32_e32 v241, 0xffff0000, v237
	v_pk_mul_f32 v[82:83], v[82:83], v[240:241]
	v_lshlrev_b32_e32 v244, 16, v238
	v_and_b32_e32 v245, 0xffff0000, v238
	v_pk_mul_f32 v[84:85], v[84:85], v[244:245]
	v_lshlrev_b32_e32 v246, 16, v239
	v_and_b32_e32 v247, 0xffff0000, v239
	v_pk_mul_f32 v[86:87], v[86:87], v[246:247]
	v_lshlrev_b32_e32 v252, 16, v4
	v_and_b32_e32 v253, 0xffff0000, v4
	v_pk_add_f32 v[80:81], v[80:81], v[252:253]
	v_lshlrev_b32_e32 v178, 16, v5
	v_and_b32_e32 v179, 0xffff0000, v5
	v_pk_add_f32 v[82:83], v[82:83], v[178:179]
	v_lshlrev_b32_e32 v240, 16, v6
	v_and_b32_e32 v241, 0xffff0000, v6
	v_pk_add_f32 v[84:85], v[84:85], v[240:241]
	v_lshlrev_b32_e32 v244, 16, v7
	v_and_b32_e32 v245, 0xffff0000, v7
	v_pk_add_f32 v[86:87], v[86:87], v[244:245]
	v_cvt_pk_bf16_f32 v236, v80, v81
	v_cvt_pk_bf16_f32 v237, v82, v83
	v_cvt_pk_bf16_f32 v238, v84, v85
	v_cvt_pk_bf16_f32 v239, v86, v87
	s_mov_b32 s58, 0x48000
	v_lshl_add_u64 v[246:247], v[172:173], 0, s[58:59]
	global_store_dwordx4 v[246:247], v[236:239], off sc1
	s_waitcnt vmcnt(17)
	v_lshlrev_b32_e32 v252, 16, v0
	v_and_b32_e32 v253, 0xffff0000, v0
	v_pk_mul_f32 v[88:89], v[88:89], v[252:253]
	v_lshlrev_b32_e32 v178, 16, v1
	v_and_b32_e32 v179, 0xffff0000, v1
	v_pk_mul_f32 v[90:91], v[90:91], v[178:179]
	v_lshlrev_b32_e32 v240, 16, v2
	v_and_b32_e32 v241, 0xffff0000, v2
	v_pk_mul_f32 v[92:93], v[92:93], v[240:241]
	v_lshlrev_b32_e32 v244, 16, v3
	v_and_b32_e32 v245, 0xffff0000, v3
	v_pk_mul_f32 v[94:95], v[94:95], v[244:245]
	v_lshlrev_b32_e32 v246, 16, v128
	v_and_b32_e32 v247, 0xffff0000, v128
	v_pk_add_f32 v[88:89], v[88:89], v[246:247]
	v_lshlrev_b32_e32 v252, 16, v129
	v_and_b32_e32 v253, 0xffff0000, v129
	v_pk_add_f32 v[90:91], v[90:91], v[252:253]
	v_lshlrev_b32_e32 v178, 16, v130
	v_and_b32_e32 v179, 0xffff0000, v130
	v_pk_add_f32 v[92:93], v[92:93], v[178:179]
	v_lshlrev_b32_e32 v240, 16, v131
	v_and_b32_e32 v241, 0xffff0000, v131
	v_pk_add_f32 v[94:95], v[94:95], v[240:241]
	v_cvt_pk_bf16_f32 v0, v88, v89
	v_cvt_pk_bf16_f32 v1, v90, v91
	v_cvt_pk_bf16_f32 v2, v92, v93
	v_cvt_pk_bf16_f32 v3, v94, v95
	s_mov_b32 s58, 0x48000
	v_lshl_add_u64 v[244:245], v[172:173], 0, s[58:59]
	global_store_dwordx4 v[244:245], v[0:3], off offset:256 sc1
	s_waitcnt vmcnt(13)
	v_lshlrev_b32_e32 v246, 16, v8
	v_and_b32_e32 v247, 0xffff0000, v8
	v_pk_mul_f32 v[96:97], v[96:97], v[246:247]
	v_lshlrev_b32_e32 v252, 16, v9
	v_and_b32_e32 v253, 0xffff0000, v9
	v_pk_mul_f32 v[98:99], v[98:99], v[252:253]
	v_lshlrev_b32_e32 v178, 16, v10
	v_and_b32_e32 v179, 0xffff0000, v10
	v_pk_mul_f32 v[100:101], v[100:101], v[178:179]
	v_lshlrev_b32_e32 v240, 16, v11
	v_and_b32_e32 v241, 0xffff0000, v11
	v_pk_mul_f32 v[102:103], v[102:103], v[240:241]
	v_lshlrev_b32_e32 v244, 16, v132
	v_and_b32_e32 v245, 0xffff0000, v132
	v_pk_add_f32 v[96:97], v[96:97], v[244:245]
	v_lshlrev_b32_e32 v246, 16, v133
	v_and_b32_e32 v247, 0xffff0000, v133
	v_pk_add_f32 v[98:99], v[98:99], v[246:247]
	v_lshlrev_b32_e32 v252, 16, v134
	v_and_b32_e32 v253, 0xffff0000, v134
	v_pk_add_f32 v[100:101], v[100:101], v[252:253]
	v_lshlrev_b32_e32 v178, 16, v135
	v_and_b32_e32 v179, 0xffff0000, v135
	v_pk_add_f32 v[102:103], v[102:103], v[178:179]
	v_cvt_pk_bf16_f32 v8, v96, v97
	v_cvt_pk_bf16_f32 v9, v98, v99
	v_cvt_pk_bf16_f32 v10, v100, v101
	v_cvt_pk_bf16_f32 v11, v102, v103
	s_mov_b32 s58, 0x50000
	v_lshl_add_u64 v[240:241], v[172:173], 0, s[58:59]
	global_store_dwordx4 v[240:241], v[8:11], off sc1
	s_waitcnt vmcnt(13)
	v_lshlrev_b32_e32 v244, 16, v12
	v_and_b32_e32 v245, 0xffff0000, v12
	v_pk_mul_f32 v[104:105], v[104:105], v[244:245]
	v_lshlrev_b32_e32 v246, 16, v13
	v_and_b32_e32 v247, 0xffff0000, v13
	v_pk_mul_f32 v[106:107], v[106:107], v[246:247]
	v_lshlrev_b32_e32 v252, 16, v14
	v_and_b32_e32 v253, 0xffff0000, v14
	v_pk_mul_f32 v[108:109], v[108:109], v[252:253]
	v_lshlrev_b32_e32 v178, 16, v15
	v_and_b32_e32 v179, 0xffff0000, v15
	v_pk_mul_f32 v[110:111], v[110:111], v[178:179]
	v_lshlrev_b32_e32 v240, 16, v16
	v_and_b32_e32 v241, 0xffff0000, v16
	v_pk_add_f32 v[104:105], v[104:105], v[240:241]
	v_lshlrev_b32_e32 v244, 16, v17
	v_and_b32_e32 v245, 0xffff0000, v17
	v_pk_add_f32 v[106:107], v[106:107], v[244:245]
	v_lshlrev_b32_e32 v246, 16, v18
	v_and_b32_e32 v247, 0xffff0000, v18
	v_pk_add_f32 v[108:109], v[108:109], v[246:247]
	v_lshlrev_b32_e32 v252, 16, v19
	v_and_b32_e32 v253, 0xffff0000, v19
	v_pk_add_f32 v[110:111], v[110:111], v[252:253]
	v_cvt_pk_bf16_f32 v12, v104, v105
	v_cvt_pk_bf16_f32 v13, v106, v107
	v_cvt_pk_bf16_f32 v14, v108, v109
	v_cvt_pk_bf16_f32 v15, v110, v111
	s_mov_b32 s58, 0x50000
	v_lshl_add_u64 v[178:179], v[172:173], 0, s[58:59]
	global_store_dwordx4 v[178:179], v[12:15], off offset:256 sc1
	s_waitcnt vmcnt(11)
	v_lshlrev_b32_e32 v240, 16, v20
	v_and_b32_e32 v241, 0xffff0000, v20
	v_pk_mul_f32 v[112:113], v[112:113], v[240:241]
	v_lshlrev_b32_e32 v244, 16, v21
	v_and_b32_e32 v245, 0xffff0000, v21
	v_pk_mul_f32 v[114:115], v[114:115], v[244:245]
	v_lshlrev_b32_e32 v246, 16, v22
	v_and_b32_e32 v247, 0xffff0000, v22
	v_pk_mul_f32 v[116:117], v[116:117], v[246:247]
	v_lshlrev_b32_e32 v252, 16, v23
	v_and_b32_e32 v253, 0xffff0000, v23
	v_pk_mul_f32 v[118:119], v[118:119], v[252:253]
	v_lshlrev_b32_e32 v178, 16, v24
	v_and_b32_e32 v179, 0xffff0000, v24
	v_pk_add_f32 v[112:113], v[112:113], v[178:179]
	v_lshlrev_b32_e32 v240, 16, v25
	v_and_b32_e32 v241, 0xffff0000, v25
	v_pk_add_f32 v[114:115], v[114:115], v[240:241]
	v_lshlrev_b32_e32 v244, 16, v26
	v_and_b32_e32 v245, 0xffff0000, v26
	v_pk_add_f32 v[116:117], v[116:117], v[244:245]
	v_lshlrev_b32_e32 v246, 16, v27
	v_and_b32_e32 v247, 0xffff0000, v27
	v_pk_add_f32 v[118:119], v[118:119], v[246:247]
	v_cvt_pk_bf16_f32 v20, v112, v113
	v_cvt_pk_bf16_f32 v21, v114, v115
	v_cvt_pk_bf16_f32 v22, v116, v117
	v_cvt_pk_bf16_f32 v23, v118, v119
	s_mov_b32 s58, 0x58000
	v_lshl_add_u64 v[252:253], v[172:173], 0, s[58:59]
	global_store_dwordx4 v[252:253], v[20:23], off sc1
	s_waitcnt vmcnt(11)
	v_lshlrev_b32_e32 v178, 16, v136
	v_and_b32_e32 v179, 0xffff0000, v136
	v_pk_mul_f32 v[120:121], v[120:121], v[178:179]
	v_lshlrev_b32_e32 v240, 16, v137
	v_and_b32_e32 v241, 0xffff0000, v137
	v_pk_mul_f32 v[122:123], v[122:123], v[240:241]
	v_lshlrev_b32_e32 v244, 16, v138
	v_and_b32_e32 v245, 0xffff0000, v138
	v_pk_mul_f32 v[124:125], v[124:125], v[244:245]
	v_lshlrev_b32_e32 v246, 16, v139
	v_and_b32_e32 v247, 0xffff0000, v139
	v_pk_mul_f32 v[126:127], v[126:127], v[246:247]
	v_lshlrev_b32_e32 v252, 16, v28
	v_and_b32_e32 v253, 0xffff0000, v28
	v_pk_add_f32 v[120:121], v[120:121], v[252:253]
	v_lshlrev_b32_e32 v178, 16, v29
	v_and_b32_e32 v179, 0xffff0000, v29
	v_pk_add_f32 v[122:123], v[122:123], v[178:179]
	v_lshlrev_b32_e32 v240, 16, v30
	v_and_b32_e32 v241, 0xffff0000, v30
	v_pk_add_f32 v[124:125], v[124:125], v[240:241]
	v_lshlrev_b32_e32 v244, 16, v31
	v_and_b32_e32 v245, 0xffff0000, v31
	v_pk_add_f32 v[126:127], v[126:127], v[244:245]
	v_cvt_pk_bf16_f32 v136, v120, v121
	v_cvt_pk_bf16_f32 v137, v122, v123
	v_cvt_pk_bf16_f32 v138, v124, v125
	v_cvt_pk_bf16_f32 v139, v126, v127
	s_mov_b32 s58, 0x58000
	v_lshl_add_u64 v[246:247], v[172:173], 0, s[58:59]
	global_store_dwordx4 v[246:247], v[136:139], off offset:256 sc1
	s_branch .Lmepi_done
.Lmepi_z0:
	global_load_dwordx4 v[128:131], v[170:171], off nt
	global_load_dwordx4 v[132:135], v[170:171], off offset:256 nt
	s_mov_b32 s58, 0x20000
	v_lshl_add_u64 v[244:245], v[170:171], 0, s[58:59]
	global_load_dwordx4 v[136:139], v[244:245], off nt
	global_load_dwordx4 v[140:143], v[244:245], off offset:256 nt
	s_mov_b32 s58, 0x40000
	v_lshl_add_u64 v[246:247], v[170:171], 0, s[58:59]
	global_load_dwordx4 v[144:147], v[246:247], off nt
	global_load_dwordx4 v[148:151], v[246:247], off offset:256 nt
	s_mov_b32 s58, 0x60000
	v_lshl_add_u64 v[252:253], v[170:171], 0, s[58:59]
	global_load_dwordx4 v[152:155], v[252:253], off nt
	global_load_dwordx4 v[156:159], v[252:253], off offset:256 nt
	s_mov_b32 s58, 0x100000
	v_lshl_add_u64 v[178:179], v[170:171], 0, s[58:59]
	global_load_dwordx4 v[180:183], v[178:179], off nt
	global_load_dwordx4 v[184:187], v[178:179], off offset:256 nt
	s_mov_b32 s58, 0x120000
	v_lshl_add_u64 v[240:241], v[170:171], 0, s[58:59]
	global_load_dwordx4 v[188:191], v[240:241], off nt
	global_load_dwordx4 v[192:195], v[240:241], off offset:256 nt
	s_mov_b32 s58, 0x140000
	v_lshl_add_u64 v[244:245], v[170:171], 0, s[58:59]
	global_load_dwordx4 v[196:199], v[244:245], off nt
	global_load_dwordx4 v[236:239], v[244:245], off offset:256 nt
	s_waitcnt vmcnt(13)
	v_lshlrev_b32_e32 v246, 16, v128
	v_and_b32_e32 v247, 0xffff0000, v128
	v_pk_mul_f32 v[0:1], v[0:1], v[246:247]
	v_lshlrev_b32_e32 v252, 16, v129
	v_and_b32_e32 v253, 0xffff0000, v129
	v_pk_mul_f32 v[2:3], v[2:3], v[252:253]
	v_lshlrev_b32_e32 v178, 16, v130
	v_and_b32_e32 v179, 0xffff0000, v130
	v_pk_mul_f32 v[4:5], v[4:5], v[178:179]
	v_lshlrev_b32_e32 v240, 16, v131
	v_and_b32_e32 v241, 0xffff0000, v131
	v_pk_mul_f32 v[6:7], v[6:7], v[240:241]
	v_cvt_pk_bf16_f32 v200, v0, v1
	v_cvt_pk_bf16_f32 v201, v2, v3
	v_cvt_pk_bf16_f32 v202, v4, v5
	v_cvt_pk_bf16_f32 v203, v6, v7
	s_waitcnt vmcnt(12)
	v_lshlrev_b32_e32 v244, 16, v132
	v_and_b32_e32 v245, 0xffff0000, v132
	v_pk_mul_f32 v[8:9], v[8:9], v[244:245]
	v_lshlrev_b32_e32 v246, 16, v133
	v_and_b32_e32 v247, 0xffff0000, v133
	v_pk_mul_f32 v[10:11], v[10:11], v[246:247]
	v_lshlrev_b32_e32 v252, 16, v134
	v_and_b32_e32 v253, 0xffff0000, v134
	v_pk_mul_f32 v[12:13], v[12:13], v[252:253]
	v_lshlrev_b32_e32 v178, 16, v135
	v_and_b32_e32 v179, 0xffff0000, v135
	v_pk_mul_f32 v[14:15], v[14:15], v[178:179]
	v_cvt_pk_bf16_f32 v204, v8, v9
	v_cvt_pk_bf16_f32 v205, v10, v11
	v_cvt_pk_bf16_f32 v206, v12, v13
	v_cvt_pk_bf16_f32 v207, v14, v15
	s_mov_b32 s58, 0x160000
	v_lshl_add_u64 v[240:241], v[170:171], 0, s[58:59]
	global_load_dwordx4 v[0:3], v[240:241], off nt
	global_load_dwordx4 v[4:7], v[240:241], off offset:256 nt
	s_waitcnt vmcnt(13)
	v_lshlrev_b32_e32 v244, 16, v136
	v_and_b32_e32 v245, 0xffff0000, v136
	v_pk_mul_f32 v[16:17], v[16:17], v[244:245]
	v_lshlrev_b32_e32 v246, 16, v137
	v_and_b32_e32 v247, 0xffff0000, v137
	v_pk_mul_f32 v[18:19], v[18:19], v[246:247]
	v_lshlrev_b32_e32 v252, 16, v138
	v_and_b32_e32 v253, 0xffff0000, v138
	v_pk_mul_f32 v[20:21], v[20:21], v[252:253]
	v_lshlrev_b32_e32 v178, 16, v139
	v_and_b32_e32 v179, 0xffff0000, v139
	v_pk_mul_f32 v[22:23], v[22:23], v[178:179]
	v_cvt_pk_bf16_f32 v208, v16, v17
	v_cvt_pk_bf16_f32 v209, v18, v19
	v_cvt_pk_bf16_f32 v210, v20, v21
	v_cvt_pk_bf16_f32 v211, v22, v23
	s_waitcnt vmcnt(12)
	v_lshlrev_b32_e32 v240, 16, v140
	v_and_b32_e32 v241, 0xffff0000, v140
	v_pk_mul_f32 v[24:25], v[24:25], v[240:241]
	v_lshlrev_b32_e32 v244, 16, v141
	v_and_b32_e32 v245, 0xffff0000, v141
	v_pk_mul_f32 v[26:27], v[26:27], v[244:245]
	v_lshlrev_b32_e32 v246, 16, v142
	v_and_b32_e32 v247, 0xffff0000, v142
	v_pk_mul_f32 v[28:29], v[28:29], v[246:247]
	v_lshlrev_b32_e32 v252, 16, v143
	v_and_b32_e32 v253, 0xffff0000, v143
	v_pk_mul_f32 v[30:31], v[30:31], v[252:253]
	v_cvt_pk_bf16_f32 v212, v24, v25
	v_cvt_pk_bf16_f32 v213, v26, v27
	v_cvt_pk_bf16_f32 v214, v28, v29
	v_cvt_pk_bf16_f32 v215, v30, v31
	s_waitcnt vmcnt(11)
	v_lshlrev_b32_e32 v178, 16, v144
	v_and_b32_e32 v179, 0xffff0000, v144
	v_pk_mul_f32 v[32:33], v[32:33], v[178:179]
	v_lshlrev_b32_e32 v240, 16, v145
	v_and_b32_e32 v241, 0xffff0000, v145
	v_pk_mul_f32 v[34:35], v[34:35], v[240:241]
	v_lshlrev_b32_e32 v244, 16, v146
	v_and_b32_e32 v245, 0xffff0000, v146
	v_pk_mul_f32 v[36:37], v[36:37], v[244:245]
	v_lshlrev_b32_e32 v246, 16, v147
	v_and_b32_e32 v247, 0xffff0000, v147
	v_pk_mul_f32 v[38:39], v[38:39], v[246:247]
	v_cvt_pk_bf16_f32 v216, v32, v33
	v_cvt_pk_bf16_f32 v217, v34, v35
	v_cvt_pk_bf16_f32 v218, v36, v37
	v_cvt_pk_bf16_f32 v219, v38, v39
	s_waitcnt vmcnt(10)
	v_lshlrev_b32_e32 v252, 16, v148
	v_and_b32_e32 v253, 0xffff0000, v148
	v_pk_mul_f32 v[40:41], v[40:41], v[252:253]
	v_lshlrev_b32_e32 v178, 16, v149
	v_and_b32_e32 v179, 0xffff0000, v149
	v_pk_mul_f32 v[42:43], v[42:43], v[178:179]
	v_lshlrev_b32_e32 v240, 16, v150
	v_and_b32_e32 v241, 0xffff0000, v150
	v_pk_mul_f32 v[44:45], v[44:45], v[240:241]
	v_lshlrev_b32_e32 v244, 16, v151
	v_and_b32_e32 v245, 0xffff0000, v151
	v_pk_mul_f32 v[46:47], v[46:47], v[244:245]
	v_cvt_pk_bf16_f32 v220, v40, v41
	v_cvt_pk_bf16_f32 v221, v42, v43
	v_cvt_pk_bf16_f32 v222, v44, v45
	v_cvt_pk_bf16_f32 v223, v46, v47
	s_waitcnt vmcnt(9)
	v_lshlrev_b32_e32 v246, 16, v152
	v_and_b32_e32 v247, 0xffff0000, v152
	v_pk_mul_f32 v[48:49], v[48:49], v[246:247]
	v_lshlrev_b32_e32 v252, 16, v153
	v_and_b32_e32 v253, 0xffff0000, v153
	v_pk_mul_f32 v[50:51], v[50:51], v[252:253]
	v_lshlrev_b32_e32 v178, 16, v154
	v_and_b32_e32 v179, 0xffff0000, v154
	v_pk_mul_f32 v[52:53], v[52:53], v[178:179]
	v_lshlrev_b32_e32 v240, 16, v155
	v_and_b32_e32 v241, 0xffff0000, v155
	v_pk_mul_f32 v[54:55], v[54:55], v[240:241]
	v_cvt_pk_bf16_f32 v224, v48, v49
	v_cvt_pk_bf16_f32 v225, v50, v51
	v_cvt_pk_bf16_f32 v226, v52, v53
	v_cvt_pk_bf16_f32 v227, v54, v55
	s_waitcnt vmcnt(8)
	v_lshlrev_b32_e32 v244, 16, v156
	v_and_b32_e32 v245, 0xffff0000, v156
	v_pk_mul_f32 v[56:57], v[56:57], v[244:245]
	v_lshlrev_b32_e32 v246, 16, v157
	v_and_b32_e32 v247, 0xffff0000, v157
	v_pk_mul_f32 v[58:59], v[58:59], v[246:247]
	v_lshlrev_b32_e32 v252, 16, v158
	v_and_b32_e32 v253, 0xffff0000, v158
	v_pk_mul_f32 v[60:61], v[60:61], v[252:253]
	v_lshlrev_b32_e32 v178, 16, v159
	v_and_b32_e32 v179, 0xffff0000, v159
	v_pk_mul_f32 v[62:63], v[62:63], v[178:179]
	v_cvt_pk_bf16_f32 v156, v56, v57
	v_cvt_pk_bf16_f32 v157, v58, v59
	v_cvt_pk_bf16_f32 v158, v60, v61
	v_cvt_pk_bf16_f32 v159, v62, v63
	ds_write_b128 v177, v[156:159] offset:0
	s_waitcnt lgkmcnt(0)
	s_waitcnt vmcnt(7)
	v_lshlrev_b32_e32 v240, 16, v180
	v_and_b32_e32 v241, 0xffff0000, v180
	v_pk_mul_f32 v[64:65], v[64:65], v[240:241]
	v_lshlrev_b32_e32 v244, 16, v181
	v_and_b32_e32 v245, 0xffff0000, v181
	v_pk_mul_f32 v[66:67], v[66:67], v[244:245]
	v_lshlrev_b32_e32 v246, 16, v182
	v_and_b32_e32 v247, 0xffff0000, v182
	v_pk_mul_f32 v[68:69], v[68:69], v[246:247]
	v_lshlrev_b32_e32 v252, 16, v183
	v_and_b32_e32 v253, 0xffff0000, v183
	v_pk_mul_f32 v[70:71], v[70:71], v[252:253]
	v_cvt_pk_bf16_f32 v180, v64, v65
	v_cvt_pk_bf16_f32 v181, v66, v67
	v_cvt_pk_bf16_f32 v182, v68, v69
	v_cvt_pk_bf16_f32 v183, v70, v71
	ds_write_b128 v177, v[180:183] offset:8192
	s_waitcnt lgkmcnt(0)
	s_waitcnt vmcnt(6)
	v_lshlrev_b32_e32 v178, 16, v184
	v_and_b32_e32 v179, 0xffff0000, v184
	v_pk_mul_f32 v[72:73], v[72:73], v[178:179]
	v_lshlrev_b32_e32 v240, 16, v185
	v_and_b32_e32 v241, 0xffff0000, v185
	v_pk_mul_f32 v[74:75], v[74:75], v[240:241]
	v_lshlrev_b32_e32 v244, 16, v186
	v_and_b32_e32 v245, 0xffff0000, v186
	v_pk_mul_f32 v[76:77], v[76:77], v[244:245]
	v_lshlrev_b32_e32 v246, 16, v187
	v_and_b32_e32 v247, 0xffff0000, v187
	v_pk_mul_f32 v[78:79], v[78:79], v[246:247]
	v_cvt_pk_bf16_f32 v184, v72, v73
	v_cvt_pk_bf16_f32 v185, v74, v75
	v_cvt_pk_bf16_f32 v186, v76, v77
	v_cvt_pk_bf16_f32 v187, v78, v79
	ds_write_b128 v177, v[184:187] offset:16384
	s_waitcnt lgkmcnt(0)
	s_waitcnt vmcnt(5)
	v_lshlrev_b32_e32 v252, 16, v188
	v_and_b32_e32 v253, 0xffff0000, v188
	v_pk_mul_f32 v[80:81], v[80:81], v[252:253]
	v_lshlrev_b32_e32 v178, 16, v189
	v_and_b32_e32 v179, 0xffff0000, v189
	v_pk_mul_f32 v[82:83], v[82:83], v[178:179]
	v_lshlrev_b32_e32 v240, 16, v190
	v_and_b32_e32 v241, 0xffff0000, v190
	v_pk_mul_f32 v[84:85], v[84:85], v[240:241]
	v_lshlrev_b32_e32 v244, 16, v191
	v_and_b32_e32 v245, 0xffff0000, v191
	v_pk_mul_f32 v[86:87], v[86:87], v[244:245]
	v_cvt_pk_bf16_f32 v188, v80, v81
	v_cvt_pk_bf16_f32 v189, v82, v83
	v_cvt_pk_bf16_f32 v190, v84, v85
	v_cvt_pk_bf16_f32 v191, v86, v87
	s_mov_b32 s58, 0x48000
	v_lshl_add_u64 v[246:247], v[172:173], 0, s[58:59]
	global_store_dwordx4 v[246:247], v[188:191], off
	s_waitcnt vmcnt(5)
	v_lshlrev_b32_e32 v252, 16, v192
	v_and_b32_e32 v253, 0xffff0000, v192
	v_pk_mul_f32 v[88:89], v[88:89], v[252:253]
	v_lshlrev_b32_e32 v178, 16, v193
	v_and_b32_e32 v179, 0xffff0000, v193
	v_pk_mul_f32 v[90:91], v[90:91], v[178:179]
	v_lshlrev_b32_e32 v240, 16, v194
	v_and_b32_e32 v241, 0xffff0000, v194
	v_pk_mul_f32 v[92:93], v[92:93], v[240:241]
	v_lshlrev_b32_e32 v244, 16, v195
	v_and_b32_e32 v245, 0xffff0000, v195
	v_pk_mul_f32 v[94:95], v[94:95], v[244:245]
	v_cvt_pk_bf16_f32 v192, v88, v89
	v_cvt_pk_bf16_f32 v193, v90, v91
	v_cvt_pk_bf16_f32 v194, v92, v93
	v_cvt_pk_bf16_f32 v195, v94, v95
	s_mov_b32 s58, 0x48000
	v_lshl_add_u64 v[246:247], v[172:173], 0, s[58:59]
	global_store_dwordx4 v[246:247], v[192:195], off offset:256
	s_waitcnt vmcnt(5)
	v_lshlrev_b32_e32 v252, 16, v196
	v_and_b32_e32 v253, 0xffff0000, v196
	v_pk_mul_f32 v[96:97], v[96:97], v[252:253]
	v_lshlrev_b32_e32 v178, 16, v197
	v_and_b32_e32 v179, 0xffff0000, v197
	v_pk_mul_f32 v[98:99], v[98:99], v[178:179]
	v_lshlrev_b32_e32 v240, 16, v198
	v_and_b32_e32 v241, 0xffff0000, v198
	v_pk_mul_f32 v[100:101], v[100:101], v[240:241]
	v_lshlrev_b32_e32 v244, 16, v199
	v_and_b32_e32 v245, 0xffff0000, v199
	v_pk_mul_f32 v[102:103], v[102:103], v[244:245]
	v_cvt_pk_bf16_f32 v196, v96, v97
	v_cvt_pk_bf16_f32 v197, v98, v99
	v_cvt_pk_bf16_f32 v198, v100, v101
	v_cvt_pk_bf16_f32 v199, v102, v103
	s_mov_b32 s58, 0x50000
	v_lshl_add_u64 v[246:247], v[172:173], 0, s[58:59]
	global_store_dwordx4 v[246:247], v[196:199], off
	s_waitcnt vmcnt(5)
	v_lshlrev_b32_e32 v252, 16, v236
	v_and_b32_e32 v253, 0xffff0000, v236
	v_pk_mul_f32 v[104:105], v[104:105], v[252:253]
	v_lshlrev_b32_e32 v178, 16, v237
	v_and_b32_e32 v179, 0xffff0000, v237
	v_pk_mul_f32 v[106:107], v[106:107], v[178:179]
	v_lshlrev_b32_e32 v240, 16, v238
	v_and_b32_e32 v241, 0xffff0000, v238
	v_pk_mul_f32 v[108:109], v[108:109], v[240:241]
	v_lshlrev_b32_e32 v244, 16, v239
	v_and_b32_e32 v245, 0xffff0000, v239
	v_pk_mul_f32 v[110:111], v[110:111], v[244:245]
	v_cvt_pk_bf16_f32 v236, v104, v105
	v_cvt_pk_bf16_f32 v237, v106, v107
	v_cvt_pk_bf16_f32 v238, v108, v109
	v_cvt_pk_bf16_f32 v239, v110, v111
	s_mov_b32 s58, 0x50000
	v_lshl_add_u64 v[246:247], v[172:173], 0, s[58:59]
	global_store_dwordx4 v[246:247], v[236:239], off offset:256
	s_waitcnt vmcnt(5)
	v_lshlrev_b32_e32 v252, 16, v0
	v_and_b32_e32 v253, 0xffff0000, v0
	v_pk_mul_f32 v[112:113], v[112:113], v[252:253]
	v_lshlrev_b32_e32 v178, 16, v1
	v_and_b32_e32 v179, 0xffff0000, v1
	v_pk_mul_f32 v[114:115], v[114:115], v[178:179]
	v_lshlrev_b32_e32 v240, 16, v2
	v_and_b32_e32 v241, 0xffff0000, v2
	v_pk_mul_f32 v[116:117], v[116:117], v[240:241]
	v_lshlrev_b32_e32 v244, 16, v3
	v_and_b32_e32 v245, 0xffff0000, v3
	v_pk_mul_f32 v[118:119], v[118:119], v[244:245]
	v_cvt_pk_bf16_f32 v0, v112, v113
	v_cvt_pk_bf16_f32 v1, v114, v115
	v_cvt_pk_bf16_f32 v2, v116, v117
	v_cvt_pk_bf16_f32 v3, v118, v119
	s_mov_b32 s58, 0x58000
	v_lshl_add_u64 v[246:247], v[172:173], 0, s[58:59]
	global_store_dwordx4 v[246:247], v[0:3], off
	s_waitcnt vmcnt(5)
	v_lshlrev_b32_e32 v252, 16, v4
	v_and_b32_e32 v253, 0xffff0000, v4
	v_pk_mul_f32 v[120:121], v[120:121], v[252:253]
	v_lshlrev_b32_e32 v178, 16, v5
	v_and_b32_e32 v179, 0xffff0000, v5
	v_pk_mul_f32 v[122:123], v[122:123], v[178:179]
	v_lshlrev_b32_e32 v240, 16, v6
	v_and_b32_e32 v241, 0xffff0000, v6
	v_pk_mul_f32 v[124:125], v[124:125], v[240:241]
	v_lshlrev_b32_e32 v244, 16, v7
	v_and_b32_e32 v245, 0xffff0000, v7
	v_pk_mul_f32 v[126:127], v[126:127], v[244:245]
	v_cvt_pk_bf16_f32 v4, v120, v121
	v_cvt_pk_bf16_f32 v5, v122, v123
	v_cvt_pk_bf16_f32 v6, v124, v125
	v_cvt_pk_bf16_f32 v7, v126, v127
	s_mov_b32 s58, 0x58000
	v_lshl_add_u64 v[246:247], v[172:173], 0, s[58:59]
	global_store_dwordx4 v[246:247], v[4:7], off offset:256

	.amdhsa_kernel _Z10fwd_kernel4Args
		.amdhsa_group_segment_fixed_size 24576
		.amdhsa_private_segment_fixed_size 0
		.amdhsa_kernarg_size 456
		.amdhsa_user_sgpr_count 2
		.amdhsa_user_sgpr_dispatch_ptr 0
		.amdhsa_user_sgpr_queue_ptr 0
		.amdhsa_user_sgpr_kernarg_segment_ptr 1
		.amdhsa_user_sgpr_dispatch_id 0
		.amdhsa_user_sgpr_kernarg_preload_length 0
		.amdhsa_user_sgpr_kernarg_preload_offset 0
		.amdhsa_user_sgpr_private_segment_size 0
		.amdhsa_uses_dynamic_stack 0
		.amdhsa_enable_private_segment 0
		.amdhsa_system_sgpr_workgroup_id_x 1
		.amdhsa_system_sgpr_workgroup_id_y 0
		.amdhsa_system_sgpr_workgroup_id_z 0
		.amdhsa_system_sgpr_workgroup_info 0
		.amdhsa_system_vgpr_workitem_id 2
		.amdhsa_next_free_vgpr 256
		.amdhsa_next_free_sgpr 100
		.amdhsa_accum_offset 256
		.amdhsa_reserve_vcc 1
		.amdhsa_float_round_mode_32 0
		.amdhsa_float_round_mode_16_64 0
		.amdhsa_float_denorm_mode_32 3
		.amdhsa_float_denorm_mode_16_64 3
		.amdhsa_dx10_clamp 1
		.amdhsa_ieee_mode 1
		.amdhsa_fp16_overflow 0
		.amdhsa_tg_split 0
		.amdhsa_exception_fp_ieee_invalid_op 0
		.amdhsa_exception_fp_denorm_src 0
		.amdhsa_exception_fp_ieee_div_zero 0
		.amdhsa_exception_fp_ieee_overflow 0
		.amdhsa_exception_fp_ieee_underflow 0
		.amdhsa_exception_fp_ieee_inexact 0
		.amdhsa_exception_int_div_zero 0
	.end_amdhsa_kernel

amdhsa.kernels:
  - .agpr_count:     0
    .args:
      - .offset:         0
        .size:           200
        .value_kind:     by_value
      - .offset:         200
        .size:           4
        .value_kind:     hidden_block_count_x
      - .offset:         204
        .size:           4
        .value_kind:     hidden_block_count_y
      - .offset:         208
        .size:           4
        .value_kind:     hidden_block_count_z
      - .offset:         212
        .size:           2
        .value_kind:     hidden_group_size_x
      - .offset:         214
        .size:           2
        .value_kind:     hidden_group_size_y
      - .offset:         216
        .size:           2
        .value_kind:     hidden_group_size_z
      - .offset:         218
        .size:           2
        .value_kind:     hidden_remainder_x
      - .offset:         220
        .size:           2
        .value_kind:     hidden_remainder_y
      - .offset:         222
        .size:           2
        .value_kind:     hidden_remainder_z
      - .offset:         240
        .size:           8
        .value_kind:     hidden_global_offset_x
      - .offset:         248
        .size:           8
        .value_kind:     hidden_global_offset_y
      - .offset:         256
        .size:           8
        .value_kind:     hidden_global_offset_z
      - .offset:         264
        .size:           2
        .value_kind:     hidden_grid_dims
      - .offset:         288
        .size:           8
        .value_kind:     hidden_multigrid_sync_arg
      - .offset:         320
        .size:           4
        .value_kind:     hidden_dynamic_lds_size
    .group_segment_fixed_size: 24576
    .kernarg_segment_align: 8
    .kernarg_segment_size: 456
    .language:       OpenCL C
    .language_version:
      - 2
      - 0
    .max_flat_workgroup_size: 512
    .name:           _Z10fwd_kernel4Args
    .private_segment_fixed_size: 0
    .sgpr_count:     106
    .sgpr_spill_count: 271
    .symbol:         _Z10fwd_kernel4Args.kd
    .uniform_work_group_size: 1
    .uses_dynamic_stack: false
    .vgpr_count:     256
    .vgpr_spill_count: 0
    .wavefront_size: 64
